# MODE3 epilogue: both wave-row groups write their 64-row slabs at once into two LDS tiles (wave-uniform base shift), 4 barriers per tile instead of 8; conv weights straight from global
# speedup vs baseline: 1.0126x; 1.0034x over previous
.LBB0_1146:
	v_mov_b32_e32 v130, v224
	v_readlane_b32 s80, v255, 38
	v_readlane_b32 s81, v255, 39
	s_lshl_b32 s22, s77, 7
	v_and_b32_e32 v217, 31, v224
	s_lshl_b32 s82, s77, 9
	v_lshlrev_b32_e32 v217, 4, v217
	v_lshlrev_b32_e32 v129, 2, v130
	v_add_u32_e32 v217, s82, v217
	v_mov_b32_e32 v128, s22
	global_load_dwordx4 v[184:187], v217, s[80:81]
	s_add_u32 s82, s80, 0xb000
	s_addc_u32 s83, s81, 0
	global_load_dwordx4 v[188:191], v217, s[82:83]
	s_add_u32 s82, s80, 0x16000
	s_addc_u32 s83, s81, 0
	global_load_dwordx4 v[192:195], v217, s[82:83]
	s_add_u32 s82, s80, 0x5800
	s_addc_u32 s83, s81, 0
	global_load_dwordx4 v[196:199], v217, s[82:83]
	s_add_u32 s82, s80, 0x10800
	s_addc_u32 s83, s81, 0
	global_load_dwordx4 v[200:203], v217, s[82:83]
	s_add_u32 s82, s80, 0x1b800
	s_addc_u32 s83, s81, 0
	global_load_dwordx4 v[204:207], v217, s[82:83]
	s_and_b64 vcc, exec, s[6:7]
	s_and_b32 s82, s6, 0x10400
	v_add_u32_e32 v216, s82, v225
	s_waitcnt lgkmcnt(0)
	v_add_u32_e32 v162, 0x400, v216
	v_add_u32_e32 v163, 0x800, v216
	v_add_u32_e32 v164, 0xc00, v216
	v_add_u32_e32 v157, 0x4000, v216
	v_add_u32_e32 v158, 0x4400, v216
	v_add_u32_e32 v159, 0x4800, v216
	v_add_u32_e32 v160, 0x4c00, v216
	v_add_u32_e32 v161, 0x8000, v216
	v_add_u32_e32 v152, 0x8400, v216
	v_add_u32_e32 v153, 0x8800, v216
	v_add_u32_e32 v154, 0x8c00, v216
	v_add_u32_e32 v155, 0x9000, v216
	v_add_u32_e32 v156, 0xc000, v216
	v_add_u32_e32 v148, 0xc400, v216
	v_add_u32_e32 v149, 0xc800, v216
	v_add_u32_e32 v150, 0xcc00, v216
	v_add_u32_e32 v151, 0xd000, v216
	ds_write2_b32 v216, v88, v92 offset1:16
	ds_write2_b32 v162, v89, v93 offset0:4 offset1:20
	ds_write2_b32 v163, v90, v94 offset0:8 offset1:24
	ds_write2_b32 v164, v91, v95 offset0:12 offset1:28
	ds_write2_b32 v216, v120, v124 offset0:128 offset1:144
	ds_write2_b32 v162, v121, v125 offset0:132 offset1:148
	ds_write2_b32 v163, v122, v126 offset0:136 offset1:152
	ds_write2_b32 v164, v123, v127 offset0:140 offset1:156
	ds_write2_b32 v157, v80, v84 offset0:64 offset1:80
	ds_write2_b32 v158, v81, v85 offset0:68 offset1:84
	ds_write2_b32 v159, v82, v86 offset0:72 offset1:88
	ds_write2_b32 v160, v83, v87 offset0:76 offset1:92
	ds_write2_b32 v157, v112, v116 offset0:192 offset1:208
	ds_write2_b32 v158, v113, v117 offset0:196 offset1:212
	ds_write2_b32 v159, v114, v118 offset0:200 offset1:216
	ds_write2_b32 v160, v115, v119 offset0:204 offset1:220
	ds_write2_b32 v161, v72, v76 offset0:128 offset1:144
	ds_write2_b32 v152, v73, v77 offset0:132 offset1:148
	ds_write2_b32 v153, v74, v78 offset0:136 offset1:152
	ds_write2_b32 v154, v75, v79 offset0:140 offset1:156
	ds_write2_b32 v152, v104, v108 offset1:16
	ds_write2_b32 v153, v105, v109 offset0:4 offset1:20
	ds_write2_b32 v154, v106, v110 offset0:8 offset1:24
	ds_write2_b32 v155, v107, v111 offset0:12 offset1:28
	ds_write2_b32 v156, v64, v68 offset0:192 offset1:208
	ds_write2_b32 v148, v65, v69 offset0:196 offset1:212
	ds_write2_b32 v149, v66, v70 offset0:200 offset1:216
	ds_write2_b32 v150, v67, v71 offset0:204 offset1:220
	ds_write2_b32 v148, v96, v100 offset0:64 offset1:80
	ds_write2_b32 v149, v97, v101 offset0:68 offset1:84
	ds_write2_b32 v150, v98, v102 offset0:72 offset1:88
	ds_write2_b32 v151, v99, v103 offset0:76 offset1:92
.LBB0_1152:
	v_and_b32_e32 v131, 0x7c, v129
	v_lshlrev_b32_e32 v129, 2, v131
	v_add_u32_e32 v141, s65, v129
	v_add_u32_e32 v142, s66, v129
	v_add_u32_e32 v143, s67, v129
	v_add_u32_e32 v144, s68, v129
	v_add_u32_e32 v145, s69, v129
	v_add_u32_e32 v146, s70, v129
	v_ashrrev_i32_e32 v129, 31, v128
	s_lshl_b64 s[18:19], s[20:21], 1
	v_lshl_add_u64 v[128:129], v[128:129], 1, s[14:15]
	v_lshlrev_b32_e32 v132, 1, v131
	v_mov_b32_e32 v133, v229
	v_ashrrev_i32_e32 v140, 5, v130
	s_add_u32 s18, s61, s18
	v_lshl_add_u64 v[136:137], v[128:129], 0, v[132:133]
	v_and_b32_e32 v129, 31, v130
	s_addc_u32 s19, s62, s19
	s_add_i32 s20, s25, s24
	v_mul_lo_u32 v128, v140, s71
	v_lshlrev_b32_e32 v129, 4, v129
	s_add_i32 s20, s20, s76
	v_add3_u32 v147, v128, v129, s72
	v_lshl_add_u64 v[138:139], s[18:19], 0, v[132:133]
	v_add_u32_e32 v165, s20, v140
	s_mov_b32 s21, 0
	v_mov_b32_e32 v166, v147
	s_waitcnt vmcnt(0) lgkmcnt(0)
	s_barrier
	ds_read_b128 v[132:135], v166 offset:1040
	ds_read_b128 v[128:131], v166 offset:1552
	ds_read_b128 v[208:211], v166
	ds_read_b128 v[212:215], v166 offset:512
	ds_read_b128 v[176:179], v166 offset:2080
	ds_read_b128 v[180:183], v166 offset:2592
	s_branch .LBB0_1154

.LBB0_1160:
	v_add3_u32 v72, s20, 64, v140
	s_mov_b32 s21, 0
	v_add_u32_e32 v73, 0x10400, v147
	s_waitcnt lgkmcnt(0)
	ds_read_b128 v[68:71], v73 offset:1040
	ds_read_b128 v[64:67], v73 offset:1552
	ds_read_b128 v[92:95], v73
	ds_read_b128 v[96:99], v73 offset:512
	ds_read_b128 v[84:87], v73 offset:2080
	ds_read_b128 v[88:91], v73 offset:2592
	s_branch .LBB0_1162

.LBB0_1166:
	s_and_b64 vcc, exec, s[4:5]
	s_waitcnt lgkmcnt(0)
	s_barrier
	s_cbranch_vccnz .LBB0_1119
	ds_write2_b32 v216, v60, v56 offset1:16
	ds_write2_b32 v162, v61, v57 offset0:4 offset1:20
	ds_write2_b32 v163, v62, v58 offset0:8 offset1:24
	ds_write2_b32 v164, v63, v59 offset0:12 offset1:28
	ds_write2_b32 v216, v44, v40 offset0:128 offset1:144
	ds_write2_b32 v162, v45, v41 offset0:132 offset1:148
	ds_write2_b32 v163, v46, v42 offset0:136 offset1:152
	ds_write2_b32 v164, v47, v43 offset0:140 offset1:156
	ds_write2_b32 v157, v52, v48 offset0:64 offset1:80
	ds_write2_b32 v158, v53, v49 offset0:68 offset1:84
	ds_write2_b32 v159, v54, v50 offset0:72 offset1:88
	ds_write2_b32 v160, v55, v51 offset0:76 offset1:92
	ds_write2_b32 v157, v28, v24 offset0:192 offset1:208
	ds_write2_b32 v158, v29, v25 offset0:196 offset1:212
	ds_write2_b32 v159, v30, v26 offset0:200 offset1:216
	ds_write2_b32 v160, v31, v27 offset0:204 offset1:220
	ds_write2_b32 v161, v36, v32 offset0:128 offset1:144
	ds_write2_b32 v152, v37, v33 offset0:132 offset1:148
	ds_write2_b32 v153, v38, v34 offset0:136 offset1:152
	ds_write2_b32 v154, v39, v35 offset0:140 offset1:156
	ds_write2_b32 v152, v12, v8 offset1:16
	ds_write2_b32 v153, v13, v9 offset0:4 offset1:20
	ds_write2_b32 v154, v14, v10 offset0:8 offset1:24
	ds_write2_b32 v155, v15, v11 offset0:12 offset1:28
	ds_write2_b32 v156, v20, v16 offset0:192 offset1:208
	ds_write2_b32 v148, v21, v17 offset0:196 offset1:212
	ds_write2_b32 v149, v22, v18 offset0:200 offset1:216
	ds_write2_b32 v150, v23, v19 offset0:204 offset1:220
	ds_write2_b32 v148, v4, v0 offset0:64 offset1:80
	ds_write2_b32 v149, v5, v1 offset0:68 offset1:84
	ds_write2_b32 v150, v6, v2 offset0:72 offset1:88
	ds_write2_b32 v151, v7, v3 offset0:76 offset1:92

.LBB0_1177:
	s_addk_i32 s20, 0xc0
	v_add_u32_e32 v8, s20, v140
	s_mov_b32 s4, 0
	s_waitcnt lgkmcnt(0)
	v_add_u32_e32 v147, 0x10400, v147
	ds_read_b128 v[4:7], v147 offset:1040
	ds_read_b128 v[0:3], v147 offset:1552
	ds_read_b128 v[26:29], v147
	ds_read_b128 v[30:33], v147 offset:512
	ds_read_b128 v[18:21], v147 offset:2080
	ds_read_b128 v[22:25], v147 offset:2592
	s_branch .LBB0_1179
